# latent diff-attention: wave-uniform rescale test shortened (v_cmp -> s_cbranch_vccz, 8 -> 3 instr, one taken branch less); NaN-canonicalising self-max pair dropped
# baseline (speedup 1.0000x reference)
; template <int KW, int DV, bool NA> ...
;     ...
;     auto tile = [&](int i, const unsigned char* Kt, const unsigned char* Vt) {
;         constexpr int DT = DV / 32;
;         f32x16 p0, p1;
; #pragma unroll
;         for (int d0 = 0; d0 < 4; ++d0) {
;             const bf16x8 a0 = *(const bf16x8*)(Kt + q32 * KSTR + (kcoff + 16 * d0 + 8 * hi) * 2);
;             const bf16x8 a1 = *(const bf16x8*)(Kt + (32 + q32) * KSTR + (kcoff + 16 * d0 + 8 * hi) * 2);
;             if (d0 == 0) { p0 = __builtin_amdgcn_mfma_f32_32x32x16_bf16(a0, qf[0], negm, 0, 0, 0); p1 = __builtin_amdgcn_mfma_f32_32x32x16_bf16(a1, qf[0], negm, 0, 0, 0); }
;             else { p0 = __builtin_amdgcn_mfma_f32_32x32x16_bf16(a0, qf[d0], p0, 0, 0, 0); p1 = __builtin_amdgcn_mfma_f32_32x32x16_bf16(a1, qf[d0], p1, 0, 0, 0); }
;         }
;         if (NA && i < n1) {
;             const int kr = na_row0 + i, dr = kr - na_r + 7;
;             const int cs = min(max(na_c - 8, 0), 48);
;             const float* rb = rpbs + dr * 31 - na_c + 15;
; #pragma unroll
;             for (int r = 0; r < 16; ++r) {
;                 const int kc0 = (r & 3) + 8 * (r >> 2) + 4 * hi, kc1 = kc0 + 32;
;                 const bool ok0 = (kc0 >= cs) && (kc0 < cs + 16), ok1 = (kc1 >= cs) && (kc1 < cs + 16);
;                 p0[r] = ok0 ? p0[r] + rb[kc0] : -1e30f;
;                 p1[r] = ok1 ? p1[r] + rb[kc1] : -1e30f;
;             }
;         }
;         asm volatile("s_nop 15\n\ts_nop 7" : "+v"(p0), "+v"(p1));
;         float mxa = max3f_(p0[0], p0[1], p1[0]), mxb = max3f_(p0[2], p0[3], p1[1]);
;         mxa = max3f_(mxa, p1[2], p1[3]);
; #pragma unroll
;         for (int r = 4; r < 16; r += 4) { mxa = max3f_(mxa, p0[r], p0[r + 1]); mxb = max3f_(mxb, p0[r + 2], p0[r + 3]); mxa = max3f_(mxa, p1[r], p1[r + 1]); mxb = max3f_(mxb, p1[r + 2], p1[r + 3]); }
;         float mx = max3f_(mxa, mxb, mxb);
;         mx = xor32_max(mx);
;         if (first || __any(mx > 6.f)) {
;             const float dl = first ? mx : fmaxf(mx, 0.f);
;             const float f = first ? 0.f : __builtin_amdgcn_exp2f(-dl);
;             m_ref += dl; l_run *= f;
; #pragma unroll
;             for (int r = 0; r < 16; ++r) negm[r] = -m_ref;
;             asm volatile("" : "+v"(negm));
; #pragma unroll
;             for (int r = 0; r < 16; ++r) { p0[r] -= dl; p1[r] -= dl; }
; #pragma unroll
;             for (int d = 0; d < DT; ++d)
; #pragma unroll
.LBB0_593:
	s_mul_i32 s2, s9, 0x9400
	s_add_i32 s2, s2, 0
	v_add3_u32 v204, s2, v193, v194
	ds_read_b128 v[82:85], v204
	ds_read_b128 v[198:201], v204 offset:8704
	s_xor_b64 s[4:5], s[0:1], -1
	s_and_b64 vcc, exec, s[4:5]
	s_waitcnt lgkmcnt(1)
	v_mfma_f32_32x32x16_bf16 v[98:113], v[82:85], v[114:117], v[66:81]
	s_waitcnt lgkmcnt(0)
	v_mfma_f32_32x32x16_bf16 v[82:97], v[198:201], v[114:117], v[66:81]
	ds_read_b128 v[198:201], v204 offset:32
	s_waitcnt lgkmcnt(0)
	v_mfma_f32_32x32x16_bf16 v[98:113], v[198:201], v[118:121], v[98:113]
	ds_read_b128 v[198:201], v204 offset:8736
	s_waitcnt lgkmcnt(0)
	v_mfma_f32_32x32x16_bf16 v[82:97], v[198:201], v[118:121], v[82:97]
	ds_read_b128 v[198:201], v204 offset:64
	s_waitcnt lgkmcnt(0)
	v_mfma_f32_32x32x16_bf16 v[98:113], v[198:201], v[122:125], v[98:113]
	ds_read_b128 v[198:201], v204 offset:8768
	s_waitcnt lgkmcnt(0)
	v_mfma_f32_32x32x16_bf16 v[82:97], v[198:201], v[122:125], v[82:97]
	ds_read_b128 v[198:201], v204 offset:96
	s_waitcnt lgkmcnt(0)
	v_mfma_f32_32x32x16_bf16 v[98:113], v[198:201], v[126:129], v[98:113]
	ds_read_b128 v[198:201], v204 offset:8800
	s_waitcnt lgkmcnt(0)
	v_mfma_f32_32x32x16_bf16 v[82:97], v[198:201], v[126:129], v[82:97]
	s_nop 10
	s_nop 0
	v_max3_f32 v198, v98, v99, v82
	v_max3_f32 v199, v100, v101, v83
	v_max3_f32 v198, v198, v84, v85
	v_max3_f32 v199, v199, v104, v105
	v_max3_f32 v198, v198, v102, v103
	v_max3_f32 v199, v199, v88, v89
	v_max3_f32 v198, v198, v86, v87
	v_max3_f32 v199, v199, v108, v109
	v_max3_f32 v198, v198, v106, v107
	v_max3_f32 v199, v199, v92, v93
	v_max3_f32 v198, v198, v90, v91
	v_max3_f32 v199, v199, v112, v113
	v_max3_f32 v198, v198, v110, v111
	v_max3_f32 v199, v199, v96, v97
	v_max3_f32 v198, v198, v94, v95
	v_max3_f32 v198, v198, v199, v199
	v_mov_b32_e32 v199, v198
	s_nop 1
	v_permlane32_swap_b32_e32 v198, v199
	v_max_f32_e32 v198, v198, v199
	s_cbranch_vccz .Ldf_resc1
	v_cmp_lt_f32_e32 vcc, s80, v198
	s_cbranch_vccz .LBB0_599
.Ldf_resc1:
	v_max_f32_e32 v66, v198, v198
	v_max_f32_e32 v66, 0, v66
	v_cndmask_b32_e64 v198, v66, v198, s[0:1]
	v_exp_f32_e64 v68, -v198
	v_add_f32_e32 v196, v196, v198
	v_xor_b32_e32 v66, 0x80000000, v196
	v_mov_b32_e32 v67, v66
	v_cndmask_b32_e64 v200, v68, 0, s[0:1]
	v_mul_f32_e32 v197, v197, v200
	v_mov_b32_e32 v68, v66
	v_mov_b32_e32 v69, v66
	v_mov_b32_e32 v70, v66
	v_mov_b32_e32 v71, v66
	v_mov_b32_e32 v72, v66
	v_mov_b32_e32 v73, v66
	v_mov_b32_e32 v74, v66
	v_mov_b32_e32 v75, v66
	v_mov_b32_e32 v76, v66
	v_mov_b32_e32 v77, v66
	v_mov_b32_e32 v78, v66
	v_mov_b32_e32 v79, v66
	v_mov_b32_e32 v80, v66
	v_mov_b32_e32 v81, v66
	v_pk_add_f32 v[98:99], v[98:99], v[198:199] op_sel_hi:[1,0] neg_lo:[0,1] neg_hi:[0,1]
	v_pk_add_f32 v[82:83], v[82:83], v[198:199] op_sel_hi:[1,0] neg_lo:[0,1] neg_hi:[0,1]
	v_pk_add_f32 v[100:101], v[100:101], v[198:199] op_sel_hi:[1,0] neg_lo:[0,1] neg_hi:[0,1]
	v_pk_add_f32 v[84:85], v[84:85], v[198:199] op_sel_hi:[1,0] neg_lo:[0,1] neg_hi:[0,1]
	v_pk_add_f32 v[102:103], v[102:103], v[198:199] op_sel_hi:[1,0] neg_lo:[0,1] neg_hi:[0,1]
	v_pk_add_f32 v[86:87], v[86:87], v[198:199] op_sel_hi:[1,0] neg_lo:[0,1] neg_hi:[0,1]
	v_pk_add_f32 v[104:105], v[104:105], v[198:199] op_sel_hi:[1,0] neg_lo:[0,1] neg_hi:[0,1]
	v_pk_add_f32 v[88:89], v[88:89], v[198:199] op_sel_hi:[1,0] neg_lo:[0,1] neg_hi:[0,1]
	v_pk_add_f32 v[106:107], v[106:107], v[198:199] op_sel_hi:[1,0] neg_lo:[0,1] neg_hi:[0,1]
	v_pk_add_f32 v[90:91], v[90:91], v[198:199] op_sel_hi:[1,0] neg_lo:[0,1] neg_hi:[0,1]
	v_pk_add_f32 v[108:109], v[108:109], v[198:199] op_sel_hi:[1,0] neg_lo:[0,1] neg_hi:[0,1]
	v_pk_add_f32 v[92:93], v[92:93], v[198:199] op_sel_hi:[1,0] neg_lo:[0,1] neg_hi:[0,1]
	v_pk_add_f32 v[110:111], v[110:111], v[198:199] op_sel_hi:[1,0] neg_lo:[0,1] neg_hi:[0,1]
	v_pk_add_f32 v[94:95], v[94:95], v[198:199] op_sel_hi:[1,0] neg_lo:[0,1] neg_hi:[0,1]
	v_pk_add_f32 v[112:113], v[112:113], v[198:199] op_sel_hi:[1,0] neg_lo:[0,1] neg_hi:[0,1]
	v_pk_add_f32 v[96:97], v[96:97], v[198:199] op_sel_hi:[1,0] neg_lo:[0,1] neg_hi:[0,1]
	v_pk_mul_f32 v[64:65], v[64:65], v[200:201] op_sel_hi:[1,0]
	v_pk_mul_f32 v[62:63], v[62:63], v[200:201] op_sel_hi:[1,0]
	v_pk_mul_f32 v[60:61], v[60:61], v[200:201] op_sel_hi:[1,0]
	v_pk_mul_f32 v[58:59], v[58:59], v[200:201] op_sel_hi:[1,0]
	v_pk_mul_f32 v[56:57], v[56:57], v[200:201] op_sel_hi:[1,0]
	v_pk_mul_f32 v[54:55], v[54:55], v[200:201] op_sel_hi:[1,0]
	v_pk_mul_f32 v[52:53], v[52:53], v[200:201] op_sel_hi:[1,0]
	v_pk_mul_f32 v[50:51], v[50:51], v[200:201] op_sel_hi:[1,0]
	v_pk_mul_f32 v[48:49], v[48:49], v[200:201] op_sel_hi:[1,0]
	v_pk_mul_f32 v[46:47], v[46:47], v[200:201] op_sel_hi:[1,0]
	v_pk_mul_f32 v[44:45], v[44:45], v[200:201] op_sel_hi:[1,0]
	v_pk_mul_f32 v[42:43], v[42:43], v[200:201] op_sel_hi:[1,0]
	v_pk_mul_f32 v[40:41], v[40:41], v[200:201] op_sel_hi:[1,0]
	v_pk_mul_f32 v[38:39], v[38:39], v[200:201] op_sel_hi:[1,0]
	v_pk_mul_f32 v[36:37], v[36:37], v[200:201] op_sel_hi:[1,0]
	v_pk_mul_f32 v[34:35], v[34:35], v[200:201] op_sel_hi:[1,0]
	v_pk_mul_f32 v[32:33], v[32:33], v[200:201] op_sel_hi:[1,0]
	v_pk_mul_f32 v[30:31], v[30:31], v[200:201] op_sel_hi:[1,0]
	v_pk_mul_f32 v[28:29], v[28:29], v[200:201] op_sel_hi:[1,0]
	v_pk_mul_f32 v[26:27], v[26:27], v[200:201] op_sel_hi:[1,0]
	v_pk_mul_f32 v[24:25], v[24:25], v[200:201] op_sel_hi:[1,0]
	v_pk_mul_f32 v[22:23], v[22:23], v[200:201] op_sel_hi:[1,0]
	v_pk_mul_f32 v[20:21], v[20:21], v[200:201] op_sel_hi:[1,0]
	v_pk_mul_f32 v[18:19], v[18:19], v[200:201] op_sel_hi:[1,0]
	v_pk_mul_f32 v[16:17], v[16:17], v[200:201] op_sel_hi:[1,0]
	v_pk_mul_f32 v[14:15], v[14:15], v[200:201] op_sel_hi:[1,0]
	v_pk_mul_f32 v[12:13], v[12:13], v[200:201] op_sel_hi:[1,0]
	v_pk_mul_f32 v[10:11], v[10:11], v[200:201] op_sel_hi:[1,0]
	v_pk_mul_f32 v[8:9], v[8:9], v[200:201] op_sel_hi:[1,0]
	v_pk_mul_f32 v[6:7], v[6:7], v[200:201] op_sel_hi:[1,0]
	v_pk_mul_f32 v[4:5], v[4:5], v[200:201] op_sel_hi:[1,0]
	v_pk_mul_f32 v[2:3], v[2:3], v[200:201] op_sel_hi:[1,0]

; template <int KW, int DV, bool NA> ...
;     ...
;             const bf16x8 a0 = *(const bf16x8*)(Kt + q32 * KSTR + (kcoff + 16 * d0 + 8 * hi) * 2);
;             const bf16x8 a1 = *(const bf16x8*)(Kt + (32 + q32) * KSTR + (kcoff + 16 * d0 + 8 * hi) * 2);
;             if (d0 == 0) { p0 = __builtin_amdgcn_mfma_f32_32x32x16_bf16(a0, qf[0], negm, 0, 0, 0); p1 = __builtin_amdgcn_mfma_f32_32x32x16_bf16(a1, qf[0], negm, 0, 0, 0); }
;             else { p0 = __builtin_amdgcn_mfma_f32_32x32x16_bf16(a0, qf[d0], p0, 0, 0, 0); p1 = __builtin_amdgcn_mfma_f32_32x32x16_bf16(a1, qf[d0], p1, 0, 0, 0); }
;         }
;         if (NA && i < n1) {
;             const int kr = na_row0 + i, dr = kr - na_r + 7;
;             const int cs = min(max(na_c - 8, 0), 48);
;             const float* rb = rpbs + dr * 31 - na_c + 15;
; #pragma unroll
;             for (int r = 0; r < 16; ++r) {
;                 const int kc0 = (r & 3) + 8 * (r >> 2) + 4 * hi, kc1 = kc0 + 32;
;                 const bool ok0 = (kc0 >= cs) && (kc0 < cs + 16), ok1 = (kc1 >= cs) && (kc1 < cs + 16);
;                 p0[r] = ok0 ? p0[r] + rb[kc0] : -1e30f;
;                 p1[r] = ok1 ? p1[r] + rb[kc1] : -1e30f;
;             }
;         }
;         asm volatile("s_nop 15\n\ts_nop 7" : "+v"(p0), "+v"(p1));
;         float mxa = max3f_(p0[0], p0[1], p1[0]), mxb = max3f_(p0[2], p0[3], p1[1]);
;         mxa = max3f_(mxa, p1[2], p1[3]);
; #pragma unroll
;         for (int r = 4; r < 16; r += 4) { mxa = max3f_(mxa, p0[r], p0[r + 1]); mxb = max3f_(mxb, p0[r + 2], p0[r + 3]); mxa = max3f_(mxa, p1[r], p1[r + 1]); mxb = max3f_(mxb, p1[r + 2], p1[r + 3]); }
;         float mx = max3f_(mxa, mxb, mxb);
;         mx = xor32_max(mx);
;         if (first || __any(mx > 6.f)) {
;             const float dl = first ? mx : fmaxf(mx, 0.f);
;             const float f = first ? 0.f : __builtin_amdgcn_exp2f(-dl);
;             m_ref += dl; l_run *= f;
; #pragma unroll
;             for (int r = 0; r < 16; ++r) negm[r] = -m_ref;
;             asm volatile("" : "+v"(negm));
; #pragma unroll
;             for (int r = 0; r < 16; ++r) { p0[r] -= dl; p1[r] -= dl; }
; #pragma unroll
;             for (int d = 0; d < DT; ++d)
; #pragma unroll
;                 for (int r = 0; r < 16; ++r) o[d][r] *= f;
;             first = false;
;         }
;     ...
;         l_run += ps;
.LBB0_602:
	v_add_f32_e32 v98, 0, v98
	v_add_f32_e32 v98, v99, v98
	v_add_f32_e32 v98, v100, v98
	v_add_f32_e32 v98, v101, v98
	v_add_f32_e32 v98, v102, v98
	v_add_f32_e32 v98, v103, v98
	v_add_f32_e32 v98, v104, v98
	v_add_f32_e32 v98, v105, v98
	v_add_f32_e32 v98, v106, v98
	v_add_f32_e32 v98, v107, v98
	v_add_f32_e32 v98, v108, v98
	v_add_f32_e32 v98, v109, v98
	v_add_f32_e32 v98, v110, v98
	v_add_f32_e32 v98, v111, v98
	v_add_f32_e32 v98, v112, v98
	v_add_f32_e32 v98, v113, v98
	v_add_f32_e32 v82, v82, v98
	v_add_f32_e32 v82, v83, v82
	v_add_f32_e32 v82, v84, v82
	v_add_f32_e32 v82, v85, v82
	v_add_f32_e32 v82, v86, v82
	v_add_f32_e32 v82, v87, v82
	v_add_f32_e32 v82, v88, v82
	v_add_f32_e32 v82, v89, v82
	v_add_f32_e32 v82, v90, v82
	v_add_f32_e32 v82, v91, v82
	v_add_f32_e32 v82, v92, v82
	v_add_f32_e32 v82, v93, v82
	v_add_f32_e32 v82, v94, v82
	v_add_f32_e32 v82, v95, v82
	v_add_f32_e32 v82, v96, v82
	v_add_f32_e32 v82, v97, v82
	v_add3_u32 v204, s13, v193, v194
	v_add_f32_e32 v197, v197, v82
	ds_read_b128 v[198:201], v204 offset:8704
	ds_read_b128 v[82:85], v204
	ds_read_b128 v[206:209], v204 offset:32
	s_waitcnt lgkmcnt(1)
	v_mfma_f32_32x32x16_bf16 v[98:113], v[82:85], v[114:117], v[66:81]
	v_mfma_f32_32x32x16_bf16 v[82:97], v[198:201], v[114:117], v[66:81]
	ds_read_b128 v[198:201], v204 offset:8736
	s_waitcnt lgkmcnt(1)
	v_mfma_f32_32x32x16_bf16 v[98:113], v[206:209], v[118:121], v[98:113]
	s_waitcnt lgkmcnt(0)
	v_mfma_f32_32x32x16_bf16 v[82:97], v[198:201], v[118:121], v[82:97]
	ds_read_b128 v[198:201], v204 offset:8768
	ds_read_b128 v[206:209], v204 offset:64
	s_waitcnt lgkmcnt(0)
	v_mfma_f32_32x32x16_bf16 v[98:113], v[206:209], v[122:125], v[98:113]
	v_mfma_f32_32x32x16_bf16 v[82:97], v[198:201], v[122:125], v[82:97]
	ds_read_b128 v[198:201], v204 offset:8800
	ds_read_b128 v[206:209], v204 offset:96
	s_waitcnt lgkmcnt(0)
	v_mfma_f32_32x32x16_bf16 v[98:113], v[206:209], v[126:129], v[98:113]
	v_mfma_f32_32x32x16_bf16 v[82:97], v[198:201], v[126:129], v[82:97]
	s_nop 10
	s_nop 0
	v_max3_f32 v198, v98, v99, v82
	v_max3_f32 v199, v100, v101, v83
	v_max3_f32 v198, v198, v84, v85
	v_max3_f32 v199, v199, v104, v105
	v_max3_f32 v198, v198, v102, v103
	v_max3_f32 v199, v199, v88, v89
	v_max3_f32 v198, v198, v86, v87
	v_max3_f32 v199, v199, v108, v109
	v_max3_f32 v198, v198, v106, v107
	v_max3_f32 v199, v199, v92, v93
	v_max3_f32 v198, v198, v90, v91
	v_max3_f32 v199, v199, v112, v113
	v_max3_f32 v198, v198, v110, v111
	v_max3_f32 v199, v199, v96, v97
	v_max3_f32 v198, v198, v94, v95
	v_max3_f32 v198, v198, v199, v199
	v_mov_b32_e32 v199, v198
	s_nop 1
	v_permlane32_swap_b32_e32 v198, v199
	v_max_f32_e32 v198, v198, v199
	v_cmp_lt_f32_e32 vcc, s80, v198
	s_cbranch_vccz .LBB0_604
	v_max_f32_e32 v66, v198, v198
	v_max_f32_e32 v198, 0, v66
	v_exp_f32_e64 v200, -v198
	v_add_f32_e32 v196, v196, v198
	v_xor_b32_e32 v66, 0x80000000, v196
	v_mov_b32_e32 v67, v66
	v_mul_f32_e32 v197, v197, v200
	v_mov_b32_e32 v68, v66
	v_mov_b32_e32 v69, v66
	v_mov_b32_e32 v70, v66
	v_mov_b32_e32 v71, v66
	v_mov_b32_e32 v72, v66
	v_mov_b32_e32 v73, v66
	v_mov_b32_e32 v74, v66
	v_mov_b32_e32 v75, v66
	v_mov_b32_e32 v76, v66
	v_mov_b32_e32 v77, v66
	v_mov_b32_e32 v78, v66
	v_mov_b32_e32 v79, v66
	v_mov_b32_e32 v80, v66
	v_mov_b32_e32 v81, v66
	v_pk_add_f32 v[98:99], v[98:99], v[198:199] op_sel_hi:[1,0] neg_lo:[0,1] neg_hi:[0,1]
	v_pk_add_f32 v[82:83], v[82:83], v[198:199] op_sel_hi:[1,0] neg_lo:[0,1] neg_hi:[0,1]
	v_pk_add_f32 v[100:101], v[100:101], v[198:199] op_sel_hi:[1,0] neg_lo:[0,1] neg_hi:[0,1]
	v_pk_add_f32 v[84:85], v[84:85], v[198:199] op_sel_hi:[1,0] neg_lo:[0,1] neg_hi:[0,1]
	v_pk_add_f32 v[102:103], v[102:103], v[198:199] op_sel_hi:[1,0] neg_lo:[0,1] neg_hi:[0,1]
	v_pk_add_f32 v[86:87], v[86:87], v[198:199] op_sel_hi:[1,0] neg_lo:[0,1] neg_hi:[0,1]
	v_pk_add_f32 v[104:105], v[104:105], v[198:199] op_sel_hi:[1,0] neg_lo:[0,1] neg_hi:[0,1]
	v_pk_add_f32 v[88:89], v[88:89], v[198:199] op_sel_hi:[1,0] neg_lo:[0,1] neg_hi:[0,1]
	v_pk_add_f32 v[106:107], v[106:107], v[198:199] op_sel_hi:[1,0] neg_lo:[0,1] neg_hi:[0,1]
	v_pk_add_f32 v[90:91], v[90:91], v[198:199] op_sel_hi:[1,0] neg_lo:[0,1] neg_hi:[0,1]
	v_pk_add_f32 v[108:109], v[108:109], v[198:199] op_sel_hi:[1,0] neg_lo:[0,1] neg_hi:[0,1]
	v_pk_add_f32 v[92:93], v[92:93], v[198:199] op_sel_hi:[1,0] neg_lo:[0,1] neg_hi:[0,1]
	v_pk_add_f32 v[110:111], v[110:111], v[198:199] op_sel_hi:[1,0] neg_lo:[0,1] neg_hi:[0,1]
	v_pk_add_f32 v[94:95], v[94:95], v[198:199] op_sel_hi:[1,0] neg_lo:[0,1] neg_hi:[0,1]
	v_pk_add_f32 v[112:113], v[112:113], v[198:199] op_sel_hi:[1,0] neg_lo:[0,1] neg_hi:[0,1]
	v_pk_add_f32 v[96:97], v[96:97], v[198:199] op_sel_hi:[1,0] neg_lo:[0,1] neg_hi:[0,1]
	v_pk_mul_f32 v[64:65], v[64:65], v[200:201] op_sel_hi:[1,0]
	v_pk_mul_f32 v[62:63], v[62:63], v[200:201] op_sel_hi:[1,0]
	v_pk_mul_f32 v[60:61], v[60:61], v[200:201] op_sel_hi:[1,0]
	v_pk_mul_f32 v[58:59], v[58:59], v[200:201] op_sel_hi:[1,0]
	v_pk_mul_f32 v[56:57], v[56:57], v[200:201] op_sel_hi:[1,0]
	v_pk_mul_f32 v[54:55], v[54:55], v[200:201] op_sel_hi:[1,0]
	v_pk_mul_f32 v[52:53], v[52:53], v[200:201] op_sel_hi:[1,0]
	v_pk_mul_f32 v[50:51], v[50:51], v[200:201] op_sel_hi:[1,0]
	v_pk_mul_f32 v[48:49], v[48:49], v[200:201] op_sel_hi:[1,0]
	v_pk_mul_f32 v[46:47], v[46:47], v[200:201] op_sel_hi:[1,0]
	v_pk_mul_f32 v[44:45], v[44:45], v[200:201] op_sel_hi:[1,0]
	v_pk_mul_f32 v[42:43], v[42:43], v[200:201] op_sel_hi:[1,0]
	v_pk_mul_f32 v[40:41], v[40:41], v[200:201] op_sel_hi:[1,0]
	v_pk_mul_f32 v[38:39], v[38:39], v[200:201] op_sel_hi:[1,0]
	v_pk_mul_f32 v[36:37], v[36:37], v[200:201] op_sel_hi:[1,0]
	v_pk_mul_f32 v[34:35], v[34:35], v[200:201] op_sel_hi:[1,0]
	v_pk_mul_f32 v[32:33], v[32:33], v[200:201] op_sel_hi:[1,0]
	v_pk_mul_f32 v[30:31], v[30:31], v[200:201] op_sel_hi:[1,0]
	v_pk_mul_f32 v[28:29], v[28:29], v[200:201] op_sel_hi:[1,0]
	v_pk_mul_f32 v[26:27], v[26:27], v[200:201] op_sel_hi:[1,0]
	v_pk_mul_f32 v[24:25], v[24:25], v[200:201] op_sel_hi:[1,0]
	v_pk_mul_f32 v[22:23], v[22:23], v[200:201] op_sel_hi:[1,0]
	v_pk_mul_f32 v[20:21], v[20:21], v[200:201] op_sel_hi:[1,0]
	v_pk_mul_f32 v[18:19], v[18:19], v[200:201] op_sel_hi:[1,0]
	v_pk_mul_f32 v[16:17], v[16:17], v[200:201] op_sel_hi:[1,0]
	v_pk_mul_f32 v[14:15], v[14:15], v[200:201] op_sel_hi:[1,0]
	v_pk_mul_f32 v[12:13], v[12:13], v[200:201] op_sel_hi:[1,0]
	v_pk_mul_f32 v[10:11], v[10:11], v[200:201] op_sel_hi:[1,0]
	v_pk_mul_f32 v[8:9], v[8:9], v[200:201] op_sel_hi:[1,0]
	v_pk_mul_f32 v[6:7], v[6:7], v[200:201] op_sel_hi:[1,0]
	v_pk_mul_f32 v[4:5], v[4:5], v[200:201] op_sel_hi:[1,0]
	v_pk_mul_f32 v[2:3], v[2:3], v[200:201] op_sel_hi:[1,0]
